# G3 items dealt per XCD, w_gla_out tiles of ph8 slack moved to ph6 slack, seam ph8->9 XCD-local (5 local seams)
# speedup vs baseline: 1.0222x; 1.0057x over previous
; __device__ __forceinline__ int defer_tile(int k) { if (k < 1408) return 1472 + k; k -= 1408; if (k < 704) return 3584 + k; k -= 704; if (k < 256) return 4544 + k; k -= 256; if (k < 64) return 4864 + k; k -= 64; return 5696 + k; }
; #define PHASE(k, ...) if (EN(k) && lo <= (k) && (k) < hi) { constexpr bool dup_ = false; (void)dup_; __VA_ARGS__ if ((k) + 1 < hi) GRID_SYNC(); } if (DUP(k) && lo <= (k) && (k) < hi) { constexpr bool dup_ = true; (void)dup_; __VA_ARGS__ GRID_SYNC(); }
; __device__ __forceinline__ void transpose_tile(const float* src, int ldsrc, int k0, int n0, bf16_t* dst, int ldd, const float* gain, int rowmode, float* T) {
;     ...
;         *(u32x4*)(dst + (size_t)row * ldd + k0 + k8) = w; }
;     __syncthreads();
; __global__ void __launch_bounds__(NT, 2) fwd_kernel(Params P) {
;     ...
;     PHASE(6, gla_g1(P, lds); if (!dup_ && G == 256 && bx >= 64) { __syncthreads(); for (int k = bx - 64; k < N_DEFER; k += 384) weight_tile(P, defer_tile(k), (float*)lds); } )
.LBB0_1982:
	v_mad_u64_u32 v[16:17], s[36:37], s38, v15, 0
	v_mov_b32_e32 v14, v17
	v_mad_u64_u32 v[14:15], s[36:37], s39, v15, v[14:15]
	v_mov_b32_e32 v17, v14
	v_lshl_add_u64 v[14:15], v[16:17], 1, s[34:35]
	s_lshl_b32 s30, s41, 1
	v_lshl_add_u64 v[14:15], v[14:15], 0, s[30:31]
	v_lshl_add_u64 v[14:15], v[14:15], 0, v[6:7]
	s_add_i32 s30, s79, 0xffffff40
	s_cmpk_lt_i32 s79, 0x900
	s_cselect_b32 s30, s79, s30
	s_add_i32 s3, s30, 0x180
	s_cmpk_lt_i32 s79, 0x9c0
	global_store_dwordx4 v[14:15], v[0:3], off
	s_barrier
	s_cbranch_scc0 .LBB0_2019

; #define G3_LOAD_S(it_) do { _Pragma("unroll") for (int s_ = 0; s_ < 4; ++s_) _Pragma("unroll") for (int nt_ = 0; nt_ < 2; ++nt_) \
;         sfp[s_][nt_] = *(const bf16x8*)(SpT + ((size_t)(it_) * 256 + 32 * wid + 16 * nt_ + fr) * 128 + 32 * s_ + 8 * fq); } while (0)
; __device__ __forceinline__ void gla_g3(const Params& P, unsigned char* lds) {
;     const int tid = threadIdx.x, wid = tid >> 6, lane = tid & 63, fr = lane & 15, fq = lane >> 4;
;     const bf16_t* qg = (const bf16_t*)(P.ws + O_Q); const bf16_t* kg = (const bf16_t*)(P.ws + O_K); const bf16_t* gg = (const bf16_t*)(P.ws + O_G);
;     const bf16_t* vT = (const bf16_t*)(P.ws + O_VT); const bf16_t* SpT = (const bf16_t*)(P.ws + O_KVT); bf16_t* og = (bf16_t*)(P.ws + O_OG);
;     const float* bsh = (const float*)(lds + L_BSH); bf16_t* qd = (bf16_t*)(lds + L_QD); bf16_t* kin = (bf16_t*)(lds + L_KIN); bf16_t* Psh = (bf16_t*)(lds + L_PSH); float* ssh = (float*)(lds + L_SSQ);
;     bf16x8 sfp[4][2];
;     ...
;     if ((int)blockIdx.x < NITEM) G3_LOAD_S(blockIdx.x);
.LBB0_2136:
	s_cmp_lt_i32 s56, 9
	s_waitcnt lgkmcnt(0)
	s_cselect_b64 s[6:7], -1, 0
	s_cmp_gt_i32 s57, 8
	s_cselect_b64 s[8:9], -1, 0
	s_and_b64 s[6:7], s[6:7], s[8:9]
	s_andn2_b64 vcc, exec, s[6:7]
	s_cbranch_vccnz .LBB0_2276
	s_load_dwordx2 s[44:45], s[0:1], 0xc0
	s_waitcnt vmcnt(0)
	v_lshrrev_b32_e32 v36, 6, v210
	v_bfe_u32 v37, v210, 4, 2
	v_and_b32_e32 v103, 15, v210
	v_lshlrev_b32_e32 v34, 5, v36
	s_waitcnt lgkmcnt(0)
	s_add_u32 s14, s44, 0xbacdc00
	s_addc_u32 s15, s45, 0
	s_cmpk_lt_i32 s2, 0x440
	s_cselect_b64 s[6:7], -1, 0
	s_cmpk_gt_i32 s2, 0x43f
	v_lshlrev_b32_e32 v32, 4, v37
	s_cbranch_scc1 .LBB0_2139
	s_and_b32 s3, s2, 7
	s_lshr_b32 s8, s3, 1
	s_lshl_b32 s8, s8, 8
	s_and_b32 s3, s3, 1
	s_lshl_b32 s3, s3, 5
	s_or_b32 s8, s8, s3
	s_lshr_b32 s3, s2, 3
	s_add_i32 s8, s8, s3
	s_cmpk_eq_i32 s58, 0x100
	s_cselect_b32 s8, s8, s2
	s_mov_b32 s9, 0
	s_lshl_b64 s[8:9], s[8:9], 8
	s_mov_b32 s3, 0
	v_mov_b32_e32 v35, 0
	v_lshl_add_u64 v[0:1], s[8:9], 0, v[34:35]
	v_or_b32_e32 v0, v0, v103
	v_mov_b32_e32 v33, v35
	v_lshl_add_u64 v[2:3], s[14:15], 0, v[32:33]
	v_lshlrev_b64 v[0:1], 8, v[0:1]
	v_lshl_add_u64 v[38:39], v[2:3], 0, v[0:1]
	v_or_b32_e32 v0, 0x1000, v0
	v_lshl_add_u64 v[40:41], v[2:3], 0, v[0:1]
	global_load_dwordx4 v[0:3], v[38:39], off
	global_load_dwordx4 v[4:7], v[38:39], off offset:64
	global_load_dwordx4 v[8:11], v[40:41], off
	global_load_dwordx4 v[12:15], v[40:41], off offset:64
	global_load_dwordx4 v[16:19], v[38:39], off offset:128
	global_load_dwordx4 v[20:23], v[38:39], off offset:192
	global_load_dwordx4 v[24:27], v[40:41], off offset:128
	global_load_dwordx4 v[28:31], v[40:41], off offset:192
; __device__ __forceinline__ Item decode_item(int it) { Item I; if (it < 1024) { const int b = it >> 8; I.h = (it >> 6) & 3; I.row0 = b * SEQ + (it & 63) * 64; I.L = 64; } else { const int j = it - 1024; I.h = j & 3; I.row0 = MP_ROWS + (j >> 2) * 16; I.L = 16; } I.j = it; return I; }
; #define G3_LOAD_S(it_) do { _Pragma("unroll") for (int s_ = 0; s_ < 4; ++s_) _Pragma("unroll") for (int nt_ = 0; nt_ < 2; ++nt_) \
;         sfp[s_][nt_] = *(const bf16x8*)(SpT + ((size_t)(it_) * 256 + 32 * wid + 16 * nt_ + fr) * 128 + 32 * s_ + 8 * fq); } while (0)
; __device__ __forceinline__ void gla_g3(const Params& P, unsigned char* lds) {
;     const int tid = threadIdx.x, wid = tid >> 6, lane = tid & 63, fr = lane & 15, fq = lane >> 4;
;     const bf16_t* qg = (const bf16_t*)(P.ws + O_Q); const bf16_t* kg = (const bf16_t*)(P.ws + O_K); const bf16_t* gg = (const bf16_t*)(P.ws + O_G);
;     const bf16_t* vT = (const bf16_t*)(P.ws + O_VT); const bf16_t* SpT = (const bf16_t*)(P.ws + O_KVT); bf16_t* og = (bf16_t*)(P.ws + O_OG);
;     const float* bsh = (const float*)(lds + L_BSH); bf16_t* qd = (bf16_t*)(lds + L_QD); bf16_t* kin = (bf16_t*)(lds + L_KIN); bf16_t* Psh = (bf16_t*)(lds + L_PSH); float* ssh = (float*)(lds + L_SSQ);
;     bf16x8 sfp[4][2];
;     ...
;     if ((int)blockIdx.x < NITEM) G3_LOAD_S(blockIdx.x);
;     for (int it = blockIdx.x; it < NITEM; it += gridDim.x) {
;         const Item I = decode_item(it);
;         compute_b(P, I, lds);
.LBB0_2139:
	s_andn2_b64 vcc, exec, s[6:7]
	v_lshrrev_b32_e32 v102, 4, v210
	s_cbranch_vccnz .LBB0_2181
	v_lshlrev_b32_e32 v33, 3, v210
	v_and_b32_e32 v33, 0x78, v33
	v_lshlrev_b32_e32 v64, 1, v33
	v_mov_b32_e32 v65, 0
	v_lshl_add_u64 v[38:39], s[44:45], 0, v[64:65]
	s_mov_b64 s[16:17], 0x510dc00
	s_add_u32 s3, s44, 0x9a2dc00
	v_lshrrev_b32_e32 v40, 7, v210
	v_lshl_add_u64 v[66:67], v[38:39], 0, s[16:17]
	s_mov_b64 s[16:17], 0x614dc00
	s_addc_u32 s78, s45, 0
	v_lshlrev_b32_e32 v108, 4, v40
	v_lshl_add_u64 v[68:69], v[38:39], 0, s[16:17]
	v_lshl_add_u32 v38, v33, 2, 0
	v_lshlrev_b32_e32 v33, 1, v36
	s_add_u32 s79, s44, 0x308dc00
	v_and_b32_e32 v57, 2, v33
	v_or_b32_e32 v33, v108, v103
	v_add_u32_e32 v60, 0, v32
	s_movk_i32 s16, 0x110
	s_addc_u32 s80, s45, 0
	s_add_i32 s46, 0, 0x14400
	v_mad_u32_u24 v127, v33, s16, v60
	v_mov_b32_e32 v33, v65
	v_lshl_add_u32 v104, v103, 2, s46
	v_sub_u32_e32 v39, v38, v64
	v_lshl_add_u64 v[72:73], s[14:15], 0, v[32:33]
	v_and_b32_e32 v33, 0x3c0, v210
	v_lshlrev_b32_e32 v64, 6, v36
	v_lshlrev_b32_e32 v58, 2, v37
	v_lshlrev_b32_e32 v70, 3, v37
	v_mov_b32_e32 v71, v65
	v_cmp_eq_u32_e64 s[14:15], 0, v37
	v_lshl_add_u32 v129, v33, 2, v104
	v_lshl_add_u64 v[36:37], s[44:45], 0, v[64:65]
	v_mul_u32_u24_e32 v33, 0x88, v102
	v_lshl_add_u64 v[36:37], v[36:37], 0, v[70:71]
	v_lshl_add_u32 v71, v33, 1, v39
	v_add_u32_e32 v33, 0x200, v210
	v_lshrrev_b32_e32 v130, 4, v33
	v_lshlrev_b32_e32 v35, 4, v210
	v_and_b32_e32 v107, 0x7f, v210
	s_mov_b64 s[16:17], 0x79adc00
	v_mul_u32_u24_e32 v33, 0x88, v130
	s_add_i32 s30, 0, 0x12000
	v_or_b32_e32 v135, 32, v70
	s_mov_b64 s[20:21], 0x80
	s_load_dwordx4 s[40:43], s[0:1], 0x70
	s_load_dwordx2 s[38:39], s[0:1], 0x80
	v_lshl_add_u32 v125, v107, 2, 0
	v_lshl_add_u64 v[74:75], v[36:37], 0, s[16:17]
	v_lshl_add_u32 v131, v33, 1, v39
	v_cmp_le_u32_e64 s[16:17], v57, v40
	v_lshl_or_b32 v39, v57, 4, v103
	v_cmp_lt_u32_e64 s[18:19], v57, v40
	v_add_u32_e32 v57, s30, v32
	v_mul_u32_u24_e32 v88, 0x90, v103
	v_lshlrev_b32_e32 v32, 1, v135
	v_lshl_add_u64 v[78:79], v[72:73], 0, s[20:21]
	s_mov_b64 s[20:21], 0xc0
	v_and_b32_e32 v64, 48, v35
	v_lshlrev_b32_e32 v41, 10, v40
	v_lshl_add_u32 v126, v40, 13, v125
	v_or_b32_e32 v59, v58, v108
	v_or_b32_e32 v40, 16, v39
	v_add3_u32 v136, s30, v88, v32
	v_lshl_add_u64 v[80:81], v[72:73], 0, s[20:21]
	v_lshl_add_u64 v[32:33], s[44:45], 0, v[64:65]
	s_mov_b64 s[20:21], 0x2e88000
	v_or_b32_e32 v109, 1, v108
	v_or_b32_e32 v110, 2, v108
	v_or_b32_e32 v111, 3, v108
	v_or_b32_e32 v112, 4, v108
	v_or_b32_e32 v113, 5, v108
	v_or_b32_e32 v114, 6, v108
	v_or_b32_e32 v115, 7, v108
	v_or_b32_e32 v116, 8, v108
	v_or_b32_e32 v117, 9, v108
	v_or_b32_e32 v118, 10, v108
	v_or_b32_e32 v119, 11, v108
	v_or_b32_e32 v120, 12, v108
	v_or_b32_e32 v121, 13, v108
	v_or_b32_e32 v122, 14, v108
	v_or_b32_e32 v123, 15, v108
	v_or_b32_e32 v128, v34, v103
	v_or_b32_e32 v34, v58, v34
	v_mul_u32_u24_e32 v61, 0x90, v59
	v_or_b32_e32 v132, 16, v103
	v_lshl_add_u64 v[82:83], v[32:33], 0, s[20:21]
	v_lshl_add_u32 v32, v39, 1, s30
	v_lshlrev_b32_e32 v33, 1, v40
	s_movk_i32 s6, 0x100
	s_movk_i32 s8, 0x7f
	v_lshlrev_b32_e32 v42, 6, v109
	v_lshlrev_b32_e32 v43, 6, v110
	v_lshlrev_b32_e32 v44, 6, v111
	v_lshlrev_b32_e32 v45, 6, v112
	v_lshlrev_b32_e32 v46, 6, v113
	v_lshlrev_b32_e32 v47, 6, v114
	v_lshlrev_b32_e32 v48, 6, v115
	v_lshlrev_b32_e32 v49, 6, v116
	v_lshlrev_b32_e32 v50, 6, v117
	v_lshlrev_b32_e32 v51, 6, v118
	v_lshlrev_b32_e32 v52, 6, v119
	v_lshlrev_b32_e32 v53, 6, v120
	v_lshlrev_b32_e32 v54, 6, v121
	v_lshlrev_b32_e32 v55, 6, v122
	v_lshlrev_b32_e32 v56, 6, v123
	s_movk_i32 s10, 0xff
	s_movk_i32 s12, 0x17f
	v_lshlrev_b32_e32 v36, 9, v102
	v_lshlrev_b32_e32 v37, 9, v130
	v_mul_u32_u24_e32 v58, 0x110, v39
	v_or_b32_e32 v62, 1, v59
	v_or_b32_e32 v63, 2, v59
	v_or_b32_e32 v84, 3, v59
	v_or_b32_e32 v133, 32, v103
	v_or_b32_e32 v134, 48, v103
	v_mul_u32_u24_e32 v89, 0x110, v103
	v_add3_u32 v140, s30, v61, v33
	v_mul_u32_u24_e32 v33, 0x110, v132
	v_lshlrev_b32_e32 v64, 2, v34
	v_add_u32_e32 v165, v32, v61
	v_mbcnt_lo_u32_b32 v32, -1, 0
	s_mov_b32 s84, s96
	s_mov_b64 s[96:97], s[94:95]
	s_mov_b32 s47, 0
	v_cmp_gt_u32_e64 s[6:7], s6, v210
	v_lshrrev_b32_e32 v105, 2, v210
	v_add_u32_e32 v106, 0, v35
	v_lshl_add_u32 v124, v210, 2, 0
	v_cmp_lt_u32_e64 s[8:9], s8, v210
	v_cmp_lt_u32_e64 s[10:11], s10, v210
	v_cmp_lt_u32_e64 s[12:13], s12, v210
	v_add_u32_e32 v137, 0x900, v136
	v_add_u32_e32 v138, 0x1200, v136
	v_add_u32_e32 v139, 0x1b00, v136
	v_lshl_add_u64 v[76:77], v[72:73], 0, 64
	v_cmp_gt_u32_e64 s[20:21], v39, v59
	v_cmp_gt_u32_e64 s[22:23], v39, v62
	v_cmp_gt_u32_e64 s[24:25], v39, v63
	v_cmp_gt_u32_e64 s[26:27], v39, v84
	v_cmp_gt_u32_e64 s[28:29], v40, v59
	v_cmp_gt_u32_e64 s[30:31], v40, v62
	v_add_u32_e32 v141, 0x90, v140
	v_cmp_gt_u32_e64 s[34:35], v40, v63
	v_add_u32_e32 v142, 0x120, v140
	v_cmp_gt_u32_e64 s[36:37], v40, v84
	v_add_u32_e32 v143, 0x1b0, v140
	v_lshlrev_b32_e32 v84, 8, v128
	v_mov_b32_e32 v85, v65
	s_waitcnt lgkmcnt(0)
	v_lshl_add_u64 v[86:87], s[38:39], 0, v[64:65]
	v_lshl_add_u32 v144, v132, 2, s46
	v_lshl_add_u32 v145, v133, 2, s46
	v_lshl_add_u32 v146, v134, 2, s46
	s_lshl_b32 s81, s2, 2
	s_lshl_b32 s82, s58, 2
	s_lshl_b32 s83, s2, 4
	s_lshl_b32 s85, s58, 4
	s_lshl_b32 s86, s2, 6
	s_lshl_b32 s87, s58, 6
	s_movk_i32 s88, 0x3000
	v_add_u32_e32 v147, 0, v41
	s_mov_b32 s89, 0xbfb8aa3b
	s_mov_b32 s90, 0x800000
	s_mov_b32 s91, 0x3f317217
	s_mov_b32 s92, 0x7f800000
	s_mov_b32 s93, 0x3d800000
	v_add_u32_e32 v148, 0, v42
	v_add_u32_e32 v149, 0, v43
	v_add_u32_e32 v150, 0, v44
	v_add_u32_e32 v151, 0, v45
	v_add_u32_e32 v152, 0, v46
	v_add_u32_e32 v153, 0, v47
	v_add_u32_e32 v154, 0, v48
	v_add_u32_e32 v155, 0, v49
	v_add_u32_e32 v156, 0, v50
	v_add_u32_e32 v157, 0, v51
	v_add_u32_e32 v158, 0, v52
	v_add_u32_e32 v159, 0, v53
	v_add_u32_e32 v160, 0, v54
	v_add_u32_e32 v161, 0, v55
	v_add_u32_e32 v162, 0, v56
	v_add_u32_e32 v163, v38, v36
	v_add_u32_e32 v164, v38, v37
	s_mov_b32 s94, 0x82000
	v_add_u32_e32 v166, v57, v88
	v_add_u32_e32 v167, v60, v89
	v_add_u32_e32 v168, v60, v33
	v_mov_b32_e32 v169, 0x358637bd
	v_lshlrev_b32_e32 v88, 1, v34
	v_mov_b32_e32 v170, 0x41b17218
	v_add_u32_e32 v171, v60, v58
	v_mbcnt_hi_u32_b32 v172, -1, v32
	s_mov_b32 s48, s2
	s_and_b32 s38, s2, 7
	s_lshr_b32 s39, s2, 3
	s_lshr_b32 s60, s38, 1
	s_lshl_b32 s60, s60, 8
	s_and_b32 s38, s38, 1
	s_lshl_b32 s38, s38, 5
	s_add_i32 s38, s38, s39
	s_or_b32 s60, s60, s38
	s_cmpk_eq_i32 s58, 0x100
	s_cselect_b32 s48, s60, s2
	s_lshl_b32 s81, s48, 2
	s_lshl_b32 s83, s48, 4
	s_lshl_b32 s86, s48, 6
	s_branch .LBB0_2142
.LBB0_2141:
	s_or_b64 exec, exec, s[76:77]
	s_lshl_b32 s81, s48, 2
	s_lshl_b32 s83, s48, 4
	s_andn2_b64 vcc, exec, s[38:39]
	s_lshl_b32 s86, s48, 6
	s_barrier
	s_cbranch_vccz .LBB0_2180

; #define G3_LOAD_S(it_) do { _Pragma("unroll") for (int s_ = 0; s_ < 4; ++s_) _Pragma("unroll") for (int nt_ = 0; nt_ < 2; ++nt_) \
;         sfp[s_][nt_] = *(const bf16x8*)(SpT + ((size_t)(it_) * 256 + 32 * wid + 16 * nt_ + fr) * 128 + 32 * s_ + 8 * fq); } while (0)
; __device__ __forceinline__ void gla_g3(const Params& P, unsigned char* lds) {
;     ...
;         for (int s = 0; s < 4; ++s) { const int k8 = 32 * s + 8 * fq;
; #pragma unroll
;             for (int lt = 0; lt < 4; ++lt) { const bf16x8 qf = *(const bf16x8*)(qd + (16 * lt + fr) * 136 + k8);
;                 acc[0][lt] = __builtin_amdgcn_mfma_f32_16x16x32_bf16(sfp[s][0], qf, acc[0][lt], 0, 0, 0); acc[1][lt] = __builtin_amdgcn_mfma_f32_16x16x32_bf16(sfp[s][1], qf, acc[1][lt], 0, 0, 0); } }
;         if (it + (int)gridDim.x < NITEM) G3_LOAD_S(it + gridDim.x);
.LBB0_2160:
	ds_read_b128 v[90:93], v167 offset:38912
	ds_read_b128 v[94:97], v167 offset:38976
	s_cmpk_lg_i32 s58, 0x100
	s_cbranch_scc1 .Lg3map_orig
	s_cmpk_gt_i32 s48, 0x3ff
	s_cbranch_scc1 .Lg3map_end
	s_add_i32 s38, s48, 64
	s_xor_b32 s39, s38, s48
	s_bitcmp1_b32 s39, 8
	s_cbranch_scc0 .Lg3map_set
	s_cmp_lt_u32 s2, 64
	s_cbranch_scc0 .Lg3map_end
	s_and_b32 s38, s2, 7
	s_lshl_b32 s38, s38, 3
	s_lshr_b32 s39, s2, 3
	s_and_b32 vcc_lo, s39, 1
	s_lshl_b32 vcc_lo, vcc_lo, 2
	s_lshr_b32 s39, s39, 1
	s_add_i32 s38, s38, vcc_lo
	s_add_i32 s38, s38, s39
	s_addk_i32 s38, 0x400
	s_branch .Lg3map_set
.Lg3map_end:
	s_movk_i32 s38, 0x7fff
	s_branch .Lg3map_set
.Lg3map_orig:
	s_add_i32 s38, s48, s58
.Lg3map_set:
	s_mov_b32 s48, s38
	s_cmpk_gt_i32 s48, 0x43f
	s_cselect_b64 s[38:39], -1, 0
	s_waitcnt lgkmcnt(1)
	v_mfma_f32_16x16x32_bf16 v[44:47], v[0:3], v[90:93], v[44:47]
	s_and_b64 vcc, exec, s[38:39]
	v_mfma_f32_16x16x32_bf16 v[60:63], v[8:11], v[90:93], v[60:63]
	ds_read_b128 v[90:93], v168 offset:38912
	ds_read_b128 v[98:101], v168 offset:38976
	s_waitcnt lgkmcnt(1)
	v_mfma_f32_16x16x32_bf16 v[40:43], v[0:3], v[90:93], v[40:43]
	v_mfma_f32_16x16x32_bf16 v[56:59], v[8:11], v[90:93], v[56:59]
	ds_read_b128 v[90:93], v168 offset:43264
	ds_read_b128 v[174:177], v168 offset:43328
	s_waitcnt lgkmcnt(1)
	v_mfma_f32_16x16x32_bf16 v[36:39], v[0:3], v[90:93], v[36:39]
	v_mfma_f32_16x16x32_bf16 v[52:55], v[8:11], v[90:93], v[52:55]
	ds_read_b128 v[90:93], v168 offset:47616
	ds_read_b128 v[178:181], v168 offset:47680
	s_waitcnt lgkmcnt(1)
	v_mfma_f32_16x16x32_bf16 v[32:35], v[0:3], v[90:93], v[32:35]
	v_mfma_f32_16x16x32_bf16 v[48:51], v[8:11], v[90:93], v[48:51]
	v_mfma_f32_16x16x32_bf16 v[44:47], v[4:7], v[94:97], v[44:47]
	v_mfma_f32_16x16x32_bf16 v[60:63], v[12:15], v[94:97], v[60:63]
	ds_read_b128 v[90:93], v167 offset:39040
	ds_read_b128 v[94:97], v167 offset:39104
	v_mfma_f32_16x16x32_bf16 v[40:43], v[4:7], v[98:101], v[40:43]
	v_mfma_f32_16x16x32_bf16 v[56:59], v[12:15], v[98:101], v[56:59]
	s_waitcnt lgkmcnt(1)
	v_mfma_f32_16x16x32_bf16 v[44:47], v[16:19], v[90:93], v[44:47]
	v_mfma_f32_16x16x32_bf16 v[90:93], v[24:27], v[90:93], v[60:63]
	s_nop 2
	ds_read_b128 v[60:63], v168 offset:39040
	ds_read_b128 v[98:101], v168 offset:39104
	v_mfma_f32_16x16x32_bf16 v[36:39], v[4:7], v[174:177], v[36:39]
	v_mfma_f32_16x16x32_bf16 v[52:55], v[12:15], v[174:177], v[52:55]
	v_mfma_f32_16x16x32_bf16 v[32:35], v[4:7], v[178:181], v[32:35]
	v_mfma_f32_16x16x32_bf16 v[48:51], v[12:15], v[178:181], v[48:51]
	s_waitcnt lgkmcnt(1)
	v_mfma_f32_16x16x32_bf16 v[174:177], v[24:27], v[60:63], v[56:59]
	s_nop 2
	ds_read_b128 v[56:59], v168 offset:43392
	ds_read_b128 v[178:181], v168 offset:43456
	s_waitcnt lgkmcnt(1)
	v_mfma_f32_16x16x32_bf16 v[182:185], v[24:27], v[56:59], v[52:55]
	s_nop 2
	ds_read_b128 v[52:55], v168 offset:47744
	ds_read_b128 v[186:189], v168 offset:47808
	v_mfma_f32_16x16x32_bf16 v[40:43], v[16:19], v[60:63], v[40:43]
	v_mfma_f32_16x16x32_bf16 v[36:39], v[16:19], v[56:59], v[36:39]
	s_waitcnt lgkmcnt(1)
	v_mfma_f32_16x16x32_bf16 v[32:35], v[16:19], v[52:55], v[32:35]
	v_mfma_f32_16x16x32_bf16 v[190:193], v[24:27], v[52:55], v[48:51]
	v_mfma_f32_16x16x32_bf16 v[60:63], v[20:23], v[94:97], v[44:47]
	v_mfma_f32_16x16x32_bf16 v[56:59], v[28:31], v[94:97], v[90:93]
	v_mfma_f32_16x16x32_bf16 v[52:55], v[20:23], v[98:101], v[40:43]
	v_mfma_f32_16x16x32_bf16 v[48:51], v[28:31], v[98:101], v[174:177]
	v_mfma_f32_16x16x32_bf16 v[44:47], v[20:23], v[178:181], v[36:39]
	v_mfma_f32_16x16x32_bf16 v[40:43], v[28:31], v[178:181], v[182:185]
	s_waitcnt lgkmcnt(0)
	v_mfma_f32_16x16x32_bf16 v[36:39], v[20:23], v[186:189], v[32:35]
	v_mfma_f32_16x16x32_bf16 v[32:35], v[28:31], v[186:189], v[190:193]
	s_cbranch_vccnz .LBB0_2162
	s_mov_b32 s49, s47
	s_lshl_b64 s[62:63], s[48:49], 16
	v_lshl_add_u64 v[24:25], s[62:63], 0, v[84:85]
	v_lshl_add_u64 v[20:21], v[72:73], 0, v[24:25]
	v_or_b32_e32 v24, 0x1000, v24
	v_lshl_add_u64 v[8:9], v[72:73], 0, v[24:25]
	v_lshl_add_u64 v[12:13], v[76:77], 0, v[24:25]
	v_lshl_add_u64 v[26:27], v[78:79], 0, v[24:25]
	v_lshl_add_u64 v[28:29], v[80:81], 0, v[24:25]
	global_load_dwordx4 v[0:3], v[20:21], off
	global_load_dwordx4 v[4:7], v[20:21], off offset:64
	s_nop 0
	global_load_dwordx4 v[8:11], v[8:9], off
	s_nop 0
	global_load_dwordx4 v[12:15], v[12:13], off
	s_nop 0
	global_load_dwordx4 v[16:19], v[20:21], off offset:128
	s_nop 0
	global_load_dwordx4 v[20:23], v[20:21], off offset:192
	s_nop 0
	global_load_dwordx4 v[24:27], v[26:27], off
	s_nop 0
	global_load_dwordx4 v[28:31], v[28:29], off

; __device__ __forceinline__ int defer_tile(int k) { if (k < 1408) return 1472 + k; k -= 1408; if (k < 704) return 3584 + k; k -= 704; if (k < 256) return 4544 + k; k -= 256; if (k < 64) return 4864 + k; k -= 64; return 5696 + k; }
; #define PHASE(k, ...) if (EN(k) && lo <= (k) && (k) < hi) { constexpr bool dup_ = false; (void)dup_; __VA_ARGS__ if ((k) + 1 < hi) GRID_SYNC(); } if (DUP(k) && lo <= (k) && (k) < hi) { constexpr bool dup_ = true; (void)dup_; __VA_ARGS__ GRID_SYNC(); }
; __device__ __forceinline__ void transpose_tile(const float* src, int ldsrc, int k0, int n0, bf16_t* dst, int ldd, const float* gain, int rowmode, float* T) {
;     ...
;         *(u32x4*)(dst + (size_t)row * ldd + k0 + k8) = w; }
;     __syncthreads();
; __global__ void __launch_bounds__(NT, 2) fwd_kernel(Params P) {
;     ...
;     PHASE(6, gla_g1(P, lds); if (!dup_ && G == 256 && bx >= 64) { __syncthreads(); for (int k = bx - 64; k < N_DEFER; k += 384) weight_tile(P, defer_tile(k), (float*)lds); } )
.LBB0_2185:
	v_mad_u64_u32 v[16:17], s[34:35], s36, v14, 0
	v_mov_b32_e32 v18, v17
	v_mad_u64_u32 v[14:15], s[34:35], s37, v14, v[18:19]
	v_mov_b32_e32 v17, v14
	v_lshl_add_u64 v[14:15], v[16:17], 1, s[30:31]
	s_lshl_b32 s28, s39, 1
	v_lshl_add_u64 v[14:15], v[14:15], 0, s[28:29]
	s_add_i32 s28, s46, 0x180
	v_lshl_add_u64 v[14:15], v[14:15], 0, v[6:7]
	s_cmpk_lt_i32 s46, 0x840
	s_mov_b32 s46, s28
	global_store_dwordx4 v[14:15], v[0:3], off
	s_barrier
	s_cbranch_scc0 .LBB0_2222

; __device__ __forceinline__ unsigned xb_add(unsigned* p, unsigned v) { return __hip_atomic_fetch_add(p, v, __ATOMIC_RELAXED, __HIP_MEMORY_SCOPE_AGENT); }
; __device__ __forceinline__ void xcd_barrier(const XcdBarrier& b) {
;     asm volatile("s_waitcnt vmcnt(0)" ::: "memory");
;     __syncthreads();
;     if (threadIdx.x == 0) {
;         unsigned* bar = b.bar;
;         __builtin_amdgcn_s_waitcnt(0);
;         unsigned nloc = b.st[0], nx = b.st[1];
;         if (nloc == 0u) { xcd_barrier_complete(bar, b.x, nloc, nx); b.st[0] = nloc; b.st[1] = nx; }
;         const unsigned old = xb_add(&bar[XB_XSUB(b.x)], 1u);
;         const unsigned gen = old / nloc;
;         if (old + 1u == (gen + 1u) * nloc) {
.LBB0_2222:
	s_cmp_lt_i32 s57, 10
	s_cbranch_scc1 .LBB0_2276
	s_waitcnt vmcnt(0)
	s_barrier
	s_and_saveexec_b64 s[6:7], s[4:5]
	s_cbranch_execz .LBB0_2275
	v_mov_b32_e32 v0, 0
	global_load_dwordx4 v[6:9], v0, s[50:51] offset:256 sc1
	global_load_dwordx4 v[10:13], v0, s[50:51] offset:272 sc1
	s_lshl_b32 s3, s33, 8
	s_add_u32 s8, s50, s3
	s_addc_u32 s9, s51, 0
	v_mov_b32_e32 v3, 0x2000
	global_load_dword v4, v3, s[8:9] offset:1024 sc1
	v_mov_b32_e32 v2, 0x20000
	ds_read_b32 v2, v2
	s_waitcnt vmcnt(0) lgkmcnt(0)
	v_add_u32_e32 v14, -1, v6
	v_and_b32_e32 v1, v14, v6
	v_min_u32_e32 v15, v6, v7
	v_add_u32_e32 v14, -1, v7
	v_and_or_b32 v1, v14, v7, v1
	v_min_u32_e32 v15, v15, v8
	v_add_u32_e32 v14, -1, v8
	v_and_or_b32 v1, v14, v8, v1
	v_min_u32_e32 v15, v15, v9
	v_add_u32_e32 v14, -1, v9
	v_and_or_b32 v1, v14, v9, v1
	v_min_u32_e32 v15, v15, v10
	v_add_u32_e32 v14, -1, v10
	v_and_or_b32 v1, v14, v10, v1
	v_min_u32_e32 v15, v15, v11
	v_add_u32_e32 v14, -1, v11
	v_and_or_b32 v1, v14, v11, v1
	v_min_u32_e32 v15, v15, v12
	v_add_u32_e32 v14, -1, v12
	v_and_or_b32 v1, v14, v12, v1
	v_min_u32_e32 v15, v15, v13
	v_add_u32_e32 v14, -1, v13
	v_and_or_b32 v1, v14, v13, v1
	s_nop 0
	v_readfirstlane_b32 s10, v1
	v_readfirstlane_b32 s13, v15
	v_readfirstlane_b32 s11, v4
	v_readfirstlane_b32 s12, v2
	s_nop 1
	s_cmp_lg_u32 s10, 0
	s_cbranch_scc1 .Lseam89_full
	s_cmp_eq_u32 s13, 0
	s_cbranch_scc1 .Lseam89_full
	s_cmpk_lg_i32 s58, 0x100
	s_cbranch_scc1 .Lseam89_full
	s_cmp_eq_u32 s12, 0
	s_cbranch_scc1 .Lseam89_full
	v_mov_b32_e32 v3, 0x1000
	v_mov_b32_e32 v5, 1
	global_atomic_add v3, v3, v5, s[8:9] offset:1024 sc0
	s_waitcnt vmcnt(0)
	v_readfirstlane_b32 s13, v3
	s_add_i32 s14, s11, 1
	s_mul_i32 s14, s14, s12
	s_add_i32 s13, s13, 1
	v_mov_b32_e32 v3, 0x2000
	s_cmp_eq_u32 s13, s14
	s_cbranch_scc1 .Lseam89_lead

; __device__ __forceinline__ unsigned xb_ld(unsigned* p)              { return __hip_atomic_load(p, __ATOMIC_RELAXED, __HIP_MEMORY_SCOPE_AGENT); }
; __device__ __forceinline__ void xcd_barrier_complete(unsigned* bar, unsigned x, unsigned& nloc, unsigned& nx) {
;     const unsigned G = gridDim.x * gridDim.y * gridDim.z;
;     unsigned sum, cnt, mine, sp = 0u;
;     for (;;) {
;         sum = 0u; cnt = 0u; mine = 0u;
; #pragma unroll
;         for (unsigned j = 0; j < 16; ++j) { const unsigned c = xb_ld(&bar[XB_XCNT(j)]); sum += c; cnt += (c > 0u) ? 1u : 0u; mine = (j == x) ? c : mine; }
; __device__ __forceinline__ void xcd_barrier(const XcdBarrier& b) {
;     ...
;     if (threadIdx.x == 0) {
;         unsigned* bar = b.bar;
;         __builtin_amdgcn_s_waitcnt(0);
;         unsigned nloc = b.st[0], nx = b.st[1];
;         if (nloc == 0u) { xcd_barrier_complete(bar, b.x, nloc, nx); b.st[0] = nloc; b.st[1] = nx; }
.Lseam89_full:
	s_add_i32 s3, 0, 0x20000
	s_waitcnt vmcnt(7)
	v_mov_b32_e32 v0, s3
	s_waitcnt vmcnt(0) expcnt(0) lgkmcnt(0)
	ds_read_b32 v2, v0
	s_add_i32 s3, 0, 0x20004
	v_mov_b32_e32 v0, s3
	ds_read_b32 v0, v0
	s_waitcnt lgkmcnt(1)
	v_cmp_ne_u32_e32 vcc, 0, v2
	s_cbranch_vccnz .LBB0_2239
	s_add_u32 s8, s54, 0x3085e00
	s_addc_u32 s9, s55, 0
	s_add_u32 s10, s54, 0x3086000
	s_addc_u32 s11, s55, 0
	s_add_u32 s12, s54, 0x3086100
	s_addc_u32 s13, s55, 0
	s_add_u32 s14, s54, 0x3086200
	s_addc_u32 s15, s55, 0
	s_add_u32 s16, s54, 0x3086300
	s_addc_u32 s17, s55, 0
	s_add_u32 s18, s54, 0x3086400
	s_addc_u32 s19, s55, 0
	s_add_u32 s20, s54, 0x3086500
	s_addc_u32 s21, s55, 0
	s_add_u32 s22, s54, 0x3086600
	s_addc_u32 s23, s55, 0
	s_add_u32 s24, s54, 0x3086700
	s_addc_u32 s25, s55, 0
	s_add_u32 s26, s54, 0x3086800
	s_addc_u32 s27, s55, 0
	s_add_u32 s28, s54, 0x3086900
	s_addc_u32 s29, s55, 0
	s_add_u32 s30, s54, 0x3086a00
	s_addc_u32 s31, s55, 0
	s_add_u32 s34, s54, 0x3086b00
	s_addc_u32 s35, s55, 0
	s_add_u32 s36, s54, 0x3086c00
	s_addc_u32 s37, s55, 0
	s_add_u32 s38, s54, 0x3086d00
	s_addc_u32 s39, s55, 0
	s_add_u32 s40, s54, 0x3086e00
	s_addc_u32 s41, s55, 0
	s_mul_i32 s3, s59, s96
	s_add_u32 s42, s54, 0x3086f00
	s_mul_i32 s3, s3, s58
	s_addc_u32 s43, s55, 0
	s_mov_b32 s60, 1
	v_mov_b32_e32 v16, 0
	s_branch .LBB0_2227
